# full-128B-line LDS-DMA pieces + SGPR-base DMA issue (no VALU in load segments) in all three GEMM K-loops; unit-start vmcnt(0) drain removed
# speedup vs baseline: 1.0164x; 1.0009x over previous
; #define PG8_STAGE(bufoff, gbase, voff) do { _Pragma("unroll") for (int _i = 0; _i < 2; ++_i) \
;         __builtin_amdgcn_global_load_lds((const unsigned*)((const char*)(gbase) + (voff)[_i]), (PG8_LAS unsigned*)(lds + (bufoff) + ldsw + _i * 8192), 16, 0, 0); } while (0)
; #define PG8_BAR __builtin_amdgcn_s_barrier()
; template <class Epi, class Sched, bool ALIGN_EPI = false, bool SP2 = false>
; __device__ __forceinline__ void gemm_phase(PG8_LAS unsigned char* lds, const int tid, const Gemm g, const Sched& S, const Epi& E) {
;     const int wid = __builtin_amdgcn_readfirstlane(tid >> 6), lane = tid & 63, wr = wid >> 2, wc = wid & 3, fr = lane & 15, fq = lane >> 4;
;     const int K = g.K, nt = K / BK;
;     unsigned voffA[2], voffB[2];
; #pragma unroll
;     for (int i = 0; i < 2; ++i) { int R, C; stage_rc(tid * 16 + i * 8192, R, C); const int Rb = Epi::PERM ? ((R & ~31) + perm32(R & 31)) : R;
;         voffA[i] = (unsigned)(R * K + C) * 2u; voffB[i] = (unsigned)(Rb * K + C) * 2u; }
;     const size_t kstep = (size_t)(BK * 2);
;     const size_t hstep = (size_t)HALF * K * 2;
;     const size_t tstep = 2 * hstep;
;     const unsigned ldsw = (unsigned)wid * 1024u;
;     const int aoff = lds_byte(wr * 64 + fr, fq * 8), boff = lds_byte(wc * 32 + fr, fq * 8);
;     ...
;     if constexpr (SP2) {
;         PG8_STAGE(PG8_SB(0, 0), cB, voffB); PG8_STAGE(PG8_SB(0, 1), cB + hstep, voffB); PG8_STAGE(PG8_SA(0, 0), cA, voffA); PG8_STAGE(PG8_SA(0, 1), cA + hstep, voffA);
;         if (wr == 1) PG8_BAR;
; __global__ void __launch_bounds__(NTHR, 2) fwd_megakernel(Args a) {
;     ...
;             } else if (k == 2) {
;                 pg8::Gemm g{XB, (const bf16_t*)(lw + LW_WIN), M, INC, DM, WIN_BYTES}; pg8::StaticOrder S; S.init(M, INC, gridDim.x, blockIdx.x);
;                 pg8::EpiWin E{ACT, 1024, QKVb, a.in.q_g + L * HD, a.in.k_g + L * HD, QSCALE, RSS + (size_t)(L * 3 + 1) * M, SW + (size_t)(L * 3 + 1) * NB * NSW};
;                 pg8::gemm_phase<pg8::EpiWin, pg8::StaticOrder, true, true>(lds, tid, g, S, E);
.LBB0_118:
	v_readlane_b32 s0, v251, 54
	s_cmp_gt_i32 s0, 1
	s_mov_b64 s[0:1], -1
	s_cbranch_scc0 .LBB0_273
	v_readlane_b32 s0, v252, 30
	v_readlane_b32 s1, v252, 31
	s_andn2_b64 vcc, exec, s[0:1]
	v_readfirstlane_b32 s0, v184
	s_cbranch_vccnz .LBB0_272
	v_lshrrev_b32_e32 v236, 3, v182
	v_and_b32_e32 v237, 6, v236
	v_and_b32_e32 v238, 7, v182
	v_xor_b32_e32 v238, v238, v237
	v_lshlrev_b32_e32 v238, 4, v238
	s_lshr_b32 s90, s0, 6
	s_lshl_b32 s91, s90, 3
	v_add_u32_e32 v239, s91, v236
	v_lshl_add_u32 v245, v239, 11, v238
	v_add_u32_e32 v246, 0x20000, v245
	v_and_b32_e32 v240, 31, v239
	v_bfe_u32 v241, v240, 2, 2
	v_lshlrev_b32_e32 v241, 3, v241
	v_bfe_u32 v249, v240, 4, 1
	v_lshl_or_b32 v241, v249, 2, v241
	v_and_b32_e32 v249, 3, v240
	v_or_b32_e32 v241, v241, v249
	v_and_b32_e32 v249, 32, v239
	v_or_b32_e32 v241, v241, v249
	v_lshl_add_u32 v247, v241, 11, v238
	v_add_u32_e32 v248, 0x20000, v247
	v_and_b32_e32 v236, 15, v182
	v_lshrrev_b32_e32 v237, 4, v182
	v_and_b32_e32 v239, 6, v236
	v_xor_b32_e32 v237, v237, v239
	v_lshlrev_b32_e32 v237, 4, v237
	v_and_b32_e32 v239, 7, v236
	v_lshl_or_b32 v237, v239, 7, v237
	v_bfe_u32 v239, v236, 3, 1
	v_lshl_or_b32 v237, v239, 10, v237
	s_lshr_b32 s92, s0, 8
	s_lshl_b32 s92, s92, 13
	v_add_u32_e32 v249, s92, v237
	v_xor_b32_e32 v242, 64, v249
	s_bfe_u32 s93, s0, 0x20006
	s_lshl_b32 s93, s93, 12
	v_add_u32_e32 v240, s93, v237
	v_xor_b32_e32 v244, 64, v240
	v_add_u32_e32 v243, 0x10000, v240
	v_add_u32_e32 v244, 0x10000, v244
	v_lshlrev_b32_e32 v0, 4, v184
	v_add_u32_e32 v1, 0x2000, v0
	v_ashrrev_i32_e32 v2, 31, v1
	v_lshrrev_b32_e32 v2, 22, v2
	v_add_u32_e32 v2, v1, v2
	v_ashrrev_i32_e32 v8, 10, v2
	v_mul_i32_i24_e32 v2, 0x400, v8
	v_sub_u32_e32 v1, v1, v2
	v_lshrrev_b32_e32 v2, 4, v1
	v_bitop3_b32 v1, v2, v1, 32 bitop3:0x6c
	v_ashrrev_i32_e32 v2, 31, v1
	v_lshrrev_b32_e32 v2, 26, v2
	v_add_u32_e32 v2, v1, v2
	v_lshlrev_b32_e32 v3, 3, v8
	v_ashrrev_i32_e32 v9, 6, v2
	v_and_b32_e32 v3, -16, v3
	v_add_u32_e32 v3, v9, v3
	s_waitcnt lgkmcnt(3)
	v_and_b32_e32 v4, 3, v9
	s_mov_b32 s2, 0x1fffe0
	s_waitcnt lgkmcnt(2)
	v_lshrrev_b32_e32 v5, 2, v3
	s_waitcnt lgkmcnt(1)
	v_lshlrev_b32_e32 v6, 1, v3
	v_and_b32_e32 v2, 0xc0, v2
	v_and_or_b32 v4, v3, s2, v4
	v_and_b32_e32 v5, 4, v5
	v_and_b32_e32 v6, 24, v6
	v_sub_u32_e32 v1, v1, v2
	v_or3_b32 v4, v4, v5, v6
	v_lshlrev_b32_e32 v5, 5, v8
	v_ashrrev_i16_sdwa v1, v223, sext(v1) dst_sel:DWORD dst_unused:UNUSED_PAD src0_sel:DWORD src1_sel:BYTE_0
	v_and_b32_e32 v5, 32, v5
	v_bfe_i32 v10, v1, 0, 16
	v_add_lshl_u32 v1, v5, v10, 1
	v_mov_b32_e32 v160, v248
	v_mov_b32_e32 v162, v246
	v_bfe_i32 v1, v184, 27, 1
	v_lshrrev_b32_e32 v1, 22, v1
	v_add_u32_e32 v1, v0, v1
	v_and_b32_e32 v1, 0xfffffc00, v1
	v_sub_u32_e32 v0, v0, v1
	v_lshrrev_b32_e32 v1, 4, v0
	v_ashrrev_i32_e32 v2, 31, v184
	v_bitop3_b32 v0, v1, v0, 32 bitop3:0x6c
	v_lshrrev_b32_e32 v2, 26, v2
	v_ashrrev_i32_e32 v1, 31, v0
	v_add_u32_e32 v2, v184, v2
	v_lshrrev_b32_e32 v1, 26, v1
	v_ashrrev_i32_e32 v12, 6, v2
	v_readlane_b32 s1, v251, 50
	v_add_u32_e32 v1, v0, v1
	v_lshlrev_b32_e32 v2, 3, v12
	s_add_u32 s11, s1, 0x5800000
	v_readlane_b32 s1, v251, 51
	v_ashrrev_i32_e32 v11, 6, v1
	v_and_b32_e32 v2, -16, v2
	s_addc_u32 s15, s1, 0
	s_ashr_i32 s4, s0, 6
	v_add_u32_e32 v2, v11, v2
	v_and_b32_e32 v3, 3, v11
	s_ashr_i32 s1, s0, 8
	s_lshl_b32 s16, s4, 10
	v_and_or_b32 v3, v2, s2, v3
	v_lshrrev_b32_e32 v4, 2, v2
	v_lshlrev_b32_e32 v5, 1, v2
	v_and_b32_e32 v1, 0xc0, v1
	v_readlane_b32 s2, v253, 56
	v_and_b32_e32 v4, 4, v4
	v_and_b32_e32 v5, 24, v5
	v_sub_u32_e32 v0, v0, v1
	v_readlane_b32 s3, v253, 57
	s_add_u32 s2, s11, s2
	v_or3_b32 v3, v3, v4, v5
	v_lshlrev_b32_e32 v4, 5, v12
	v_ashrrev_i16_sdwa v0, v223, sext(v0) dst_sel:DWORD dst_unused:UNUSED_PAD src0_sel:DWORD src1_sel:BYTE_0
	s_addc_u32 s3, s15, s3
	v_readlane_b32 s5, v251, 23
	v_and_b32_e32 v4, 32, v4
	v_bfe_i32 v13, v0, 0, 16
	s_add_u32 s24, s2, s5
	v_readlane_b32 s2, v251, 22
	v_add_lshl_u32 v0, v4, v13, 1
	s_addc_u32 s25, s3, s2
	s_add_i32 s17, s16, 0
	v_mov_b32_e32 v164, v247
	s_add_i32 m0, s17, 0x10000
	v_readlane_b32 s20, v251, 16
	global_load_lds_dwordx4 v164, s[24:25]
	s_add_i32 m0, s17, 0x12000
	s_add_u32 s2, s24, 0x40000
	global_load_lds_dwordx4 v160, s[24:25]
	s_addc_u32 s3, s25, 0
	s_add_i32 m0, s17, 0x14000
	v_readlane_b32 s21, v251, 17
	global_load_lds_dwordx4 v164, s[2:3]
	s_add_i32 m0, s17, 0x16000
	v_readlane_b32 s22, v251, 18
	global_load_lds_dwordx4 v160, s[2:3]
	v_readlane_b32 s2, v251, 3
	v_readlane_b32 s3, v251, 4
	s_add_u32 s2, s20, s2
	s_addc_u32 s3, s21, s3
	s_add_i32 s18, s17, 0x2000
	v_mov_b32_e32 v166, v245
	v_readlane_b32 s23, v251, 19
	s_mov_b32 m0, s17
	s_add_u32 s22, s2, 0x40000
	global_load_lds_dwordx4 v166, s[2:3]
	s_mov_b32 m0, s18
	s_addc_u32 s23, s3, 0
	s_add_i32 s19, s17, 0x4000
	global_load_lds_dwordx4 v162, s[2:3]
	s_mov_b32 m0, s19
	s_add_i32 s20, s17, 0x6000
	global_load_lds_dwordx4 v166, s[22:23]
	s_mov_b32 m0, s20
	v_mov_b32_e32 v165, v169
	global_load_lds_dwordx4 v162, s[22:23]
	v_mov_b32_e32 v161, v169
	v_mov_b32_e32 v167, v169
	v_mov_b32_e32 v163, v169
	s_cmp_eq_u32 s1, 1
	s_waitcnt lgkmcnt(0)
	v_lshl_add_u64 v[6:7], s[24:25], 0, v[164:165]
	v_lshl_add_u64 v[4:5], s[24:25], 0, v[160:161]
	v_lshl_add_u64 v[0:1], s[2:3], 0, v[166:167]
	s_cselect_b64 s[44:45], -1, 0
	s_cmp_lg_u32 s1, 1
	v_lshl_add_u64 v[2:3], s[2:3], 0, v[162:163]
	s_cbranch_scc1 .LBB0_122
	s_barrier
; #define PG8_STAGE(bufoff, gbase, voff) do { _Pragma("unroll") for (int _i = 0; _i < 2; ++_i) \
;         __builtin_amdgcn_global_load_lds((const unsigned*)((const char*)(gbase) + (voff)[_i]), (PG8_LAS unsigned*)(lds + (bufoff) + ldsw + _i * 8192), 16, 0, 0); } while (0)
; #define PG8_WAIT_V(n) asm volatile("s_waitcnt vmcnt(" #n ")" ::: "memory")
; #define PG8_BAR __builtin_amdgcn_s_barrier()
; template <class Epi, class Sched, bool ALIGN_EPI = false, bool SP2 = false>
; __device__ __forceinline__ void gemm_phase(PG8_LAS unsigned char* lds, const int tid, const Gemm g, const Sched& S, const Epi& E) {
;     ...
;         if (wr == 1) PG8_BAR;
;         PG8_WAIT_V(2); PG8_BAR;
;         PG8_STAGE(PG8_SB(1, 0), cB + kstep, voffB); PG8_STAGE(PG8_SA(1, 0), cA + kstep, voffA); PG8_STAGE(PG8_SB(1, 1), cB + hstep + kstep, voffB);
;         PG8_WAIT_V(6); PG8_BAR;
.LBB0_122:
	v_readlane_b32 s22, v251, 52
	s_mul_i32 s5, s22, 3
	v_readlane_b32 s23, v251, 53
	s_lshl_b32 s46, s22, 6
	s_add_i32 s22, s5, 1
	s_ashr_i32 s23, s22, 31
	s_ashr_i32 s47, s46, 31
	s_lshl_b64 s[26:27], s[22:23], 17
	s_add_u32 s48, s8, s26
	s_addc_u32 s49, s9, s27
	s_mul_i32 s10, s22, 0x16000
	v_readlane_b32 s12, v251, 46
	s_mul_hi_i32 s5, s22, 0x16000
	s_add_u32 s21, s12, s10
	v_readlane_b32 s10, v251, 47
	s_addc_u32 s22, s10, s5
	s_and_b32 s23, s4, 3
	s_add_i32 m0, s17, 0x18000
	v_lshl_add_u64 v[6:7], v[6:7], 0, s[36:37]
	s_lshl_b32 s64, s1, 6
	s_lshl_b32 s1, s1, 13
	s_lshl_b32 s65, s23, 5
	s_lshl_b32 s10, s23, 12
	s_waitcnt vmcnt(2)
	s_barrier
	global_load_lds_dwordx4 v[6:7], off
	v_lshl_add_u64 v[4:5], v[4:5], 0, s[36:37]
	s_add_i32 m0, s17, 0x1a000
	s_add_i32 s66, s17, 0x8000
	s_add_i32 s67, s17, 0xa000
	global_load_lds_dwordx4 v[4:5], off
	v_lshl_add_u64 v[0:1], v[0:1], 0, s[36:37]
	s_mov_b32 m0, s66
	s_add_u32 s4, s24, 0x40080
	global_load_lds_dwordx4 v[0:1], off
	v_lshl_add_u64 v[0:1], v[2:3], 0, s[36:37]
	s_mov_b32 m0, s67
	s_addc_u32 s5, s25, 0
	global_load_lds_dwordx4 v[0:1], off
	s_add_i32 m0, s17, 0x1c000
	v_lshl_add_u64 v[0:1], s[4:5], 0, v[164:165]
	global_load_lds_dwordx4 v[0:1], off
	v_lshl_add_u64 v[0:1], s[4:5], 0, v[160:161]
	s_add_i32 m0, s17, 0x1e000
	v_and_b32_e32 v183, 15, v182
	global_load_lds_dwordx4 v[0:1], off
	v_lshrrev_b32_e32 v0, 1, v182
	v_and_b32_e32 v186, 24, v0
	v_lshlrev_b32_e32 v168, 1, v186
	v_lshlrev_b32_e32 v1, 2, v182
	v_lshl_or_b32 v0, v183, 6, v168
	v_and_b32_e32 v1, 32, v1
	v_bitop3_b32 v2, v0, s1, v1 bitop3:0xde
	v_mov_b32_e32 v185, v240
	v_xor_b32_e32 v0, 16, v224
	v_cmp_lt_i32_e32 vcc, v0, v226
	v_and_b32_e32 v1, 1, v12
	s_cmpk_lt_u32 s0, 0x100
	v_cndmask_b32_e32 v0, v224, v0, vcc
	v_cmp_lt_i32_e32 vcc, v225, v226
	v_lshlrev_b32_e32 v202, 2, v0
	v_readlane_b32 s0, v251, 59
	v_cndmask_b32_e32 v0, v224, v225, vcc
	v_lshlrev_b32_e32 v203, 2, v0
	v_lshlrev_b32_e32 v0, 14, v12
	v_and_b32_e32 v0, 0xffff8000, v0
	v_lshl_add_u32 v0, v11, 11, v0
	v_lshl_or_b32 v0, v1, 6, v0
	v_mov_b32_e32 v190, v245
	v_lshlrev_b32_e32 v0, 14, v8
	v_and_b32_e32 v0, 0xffff8000, v0
	s_waitcnt vmcnt(6)
	v_readlane_b32 s1, v251, 60
	v_lshl_add_u32 v0, v9, 11, v0
	v_and_b32_e32 v1, 1, v8
	v_lshl_add_u64 v[188:189], s[0:1], 0, v[168:169]
	v_lshl_or_b32 v0, v1, 6, v0
	v_readlane_b32 s0, v251, 1
	s_cselect_b64 s[50:51], -1, 0
	v_lshl_or_b32 v187, s23, 6, v186
	v_lshlrev_b32_e32 v199, 7, v183
	v_mov_b32_e32 v191, v169
	v_mov_b32_e32 v192, v246
	v_mov_b32_e32 v193, v169
	s_mov_b32 s68, 0
	v_mov_b32_e32 v204, v249
	s_lshl_b32 s69, s65, 2
	v_lshlrev_b32_e32 v205, 2, v186
	v_readlane_b32 s40, v253, 55
	s_mov_b32 s12, s0
	s_barrier
	v_readlane_b32 s1, v251, 2
	s_branch .LBB0_125

; #define PG8_STAGE(bufoff, gbase, voff) do { _Pragma("unroll") for (int _i = 0; _i < 2; ++_i) \
;         __builtin_amdgcn_global_load_lds((const unsigned*)((const char*)(gbase) + (voff)[_i]), (PG8_LAS unsigned*)(lds + (bufoff) + ldsw + _i * 8192), 16, 0, 0); } while (0)
; #define PG8_LDA(dst, b, h) do { _Pragma("unroll") for (int m = 0; m < 4; ++m) _Pragma("unroll") for (int k = 0; k < 2; ++k) dst[m][k] = *(const PG8_LAS bf16x8*)(lds + PG8_SA(b, h) + aoff + m * 2048 + k * 1024); } while (0)
; #define PG8_LDB(dst, b, h) do { _Pragma("unroll") for (int n = 0; n < 2; ++n) _Pragma("unroll") for (int k = 0; k < 2; ++k) dst[n][k] = *(const PG8_LAS bf16x8*)(lds + PG8_SB(b, h) + boff + n * 2048 + k * 1024); } while (0)
; #define PG8_MMA(ai, bj, At, Bt) do { __builtin_amdgcn_s_setprio(1); _Pragma("unroll") for (int m = 0; m < 4; ++m) _Pragma("unroll") for (int n = 0; n < 2; ++n) _Pragma("unroll") for (int k = 0; k < 2; ++k) \
;         acc[ai][bj][m][n] = __builtin_amdgcn_mfma_f32_16x16x32_bf16(Bt[n][k], At[m][k], acc[ai][bj][m][n], 0, 0, 0); __builtin_amdgcn_s_setprio(0); } while (0)
; #define PG8_WAIT_V(n) asm volatile("s_waitcnt vmcnt(" #n ")" ::: "memory")
; #define PG8_WAIT_L(n) asm volatile("s_waitcnt lgkmcnt(" #n ")" ::: "memory")
; #define PG8_BAR __builtin_amdgcn_s_barrier()
; #define PG8_SCHED __builtin_amdgcn_sched_barrier(0)
; template <class Epi, class Sched, bool ALIGN_EPI = false, bool SP2 = false>
; __device__ __forceinline__ void gemm_phase(PG8_LAS unsigned char* lds, const int tid, const Gemm g, const Sched& S, const Epi& E) {
;     ...
;             PG8_LDB(B0, 0, 0); PG8_LDB(B1, 0, 1); PG8_SCHED; PG8_LDA(At, 0, 0); PG8_STAGE(PG8_SA(1, 1), a1 + hstep, voffA);
;             PG8_WAIT_V(8); PG8_WAIT_L(0); PG8_BAR; PG8_MMA(0, 0, At, B0); PG8_MMA(0, 1, At, B1); PG8_BAR; PG8_SCHED;
;             PG8_LDA(At, 0, 1); PG8_STAGE(PG8_SB(0, 0), b2, voffB); PG8_STAGE(PG8_SB(0, 1), b2 + hstep, voffB); PG8_STAGE(PG8_SA(0, 0), a2, voffA);
;             PG8_WAIT_V(8); PG8_WAIT_L(0); PG8_BAR; PG8_MMA(1, 0, At, B0); PG8_MMA(1, 1, At, B1); PG8_BAR; PG8_SCHED;
.LBB0_130:
	s_add_u32 s4, s2, 0xfffc0080
	s_addc_u32 s5, s3, -1
	s_cmp_eq_u32 s41, 12
	s_cselect_b32 s25, s26, s5
	s_cselect_b32 s24, s27, s4
	s_cselect_b32 s5, s57, s39
	s_cselect_b32 s4, s56, s38
	ds_read_b128 v[48:51], v243
	ds_read_b128 v[52:55], v244
	ds_read_b128 v[56:59], v243 offset:2048
	ds_read_b128 v[60:63], v244 offset:2048
	ds_read_b128 v[80:83], v243 offset:16384
	ds_read_b128 v[84:87], v244 offset:16384
	ds_read_b128 v[88:91], v243 offset:18432
	ds_read_b128 v[92:95], v244 offset:18432
	s_add_i32 m0, s17, 0xc000
	ds_read_b128 v[194:197], v204
	ds_read_b128 v[206:209], v242
	ds_read_b128 v[210:213], v204 offset:2048
	ds_read_b128 v[214:217], v242 offset:2048
	ds_read_b128 v[218:221], v204 offset:4096
	ds_read_b128 v[230:233], v242 offset:4096
	ds_read_b128 v[234:237], v204 offset:6144
	ds_read_b128 v[238:241], v242 offset:6144
	global_load_lds_dwordx4 v190, s[2:3]
	s_add_i32 m0, s17, 0xe000
	s_nop 0
	global_load_lds_dwordx4 v192, s[2:3]
	s_waitcnt vmcnt(8)
	s_waitcnt lgkmcnt(0)
	s_barrier
	s_setprio 1
	s_waitcnt lgkmcnt(0)
	v_mfma_f32_16x16x32_bf16 v[156:159], v[48:51], v[194:197], v[156:159]
	v_mfma_f32_16x16x32_bf16 v[152:155], v[56:59], v[194:197], v[152:155]
	v_mfma_f32_16x16x32_bf16 v[140:143], v[48:51], v[210:213], v[140:143]
	v_mfma_f32_16x16x32_bf16 v[136:139], v[56:59], v[210:213], v[136:139]
	v_mfma_f32_16x16x32_bf16 v[124:127], v[48:51], v[218:221], v[124:127]
	v_mfma_f32_16x16x32_bf16 v[120:123], v[56:59], v[218:221], v[120:123]
	v_mfma_f32_16x16x32_bf16 v[108:111], v[48:51], v[234:237], v[108:111]
	v_mfma_f32_16x16x32_bf16 v[104:107], v[56:59], v[234:237], v[104:107]
	v_mfma_f32_16x16x32_bf16 v[156:159], v[52:55], v[206:209], v[156:159]
	v_mfma_f32_16x16x32_bf16 v[152:155], v[60:63], v[206:209], v[152:155]
	v_mfma_f32_16x16x32_bf16 v[140:143], v[52:55], v[214:217], v[140:143]
	v_mfma_f32_16x16x32_bf16 v[136:139], v[60:63], v[214:217], v[136:139]
	v_mfma_f32_16x16x32_bf16 v[124:127], v[52:55], v[230:233], v[124:127]
	v_mfma_f32_16x16x32_bf16 v[120:123], v[60:63], v[230:233], v[120:123]
	v_mfma_f32_16x16x32_bf16 v[108:111], v[52:55], v[238:241], v[108:111]
	v_mfma_f32_16x16x32_bf16 v[104:107], v[60:63], v[238:241], v[104:107]
	s_setprio 0
	s_setprio 1
	v_mfma_f32_16x16x32_bf16 v[148:151], v[80:83], v[194:197], v[148:151]
	v_mfma_f32_16x16x32_bf16 v[144:147], v[88:91], v[194:197], v[144:147]
	v_mfma_f32_16x16x32_bf16 v[132:135], v[80:83], v[210:213], v[132:135]
	v_mfma_f32_16x16x32_bf16 v[128:131], v[88:91], v[210:213], v[128:131]
	v_mfma_f32_16x16x32_bf16 v[116:119], v[80:83], v[218:221], v[116:119]
	v_mfma_f32_16x16x32_bf16 v[112:115], v[88:91], v[218:221], v[112:115]
	v_mfma_f32_16x16x32_bf16 v[100:103], v[80:83], v[234:237], v[100:103]
	v_mfma_f32_16x16x32_bf16 v[96:99], v[88:91], v[234:237], v[96:99]
	v_mfma_f32_16x16x32_bf16 v[148:151], v[84:87], v[206:209], v[148:151]
	v_mfma_f32_16x16x32_bf16 v[144:147], v[92:95], v[206:209], v[144:147]
	v_mfma_f32_16x16x32_bf16 v[132:135], v[84:87], v[214:217], v[132:135]
	v_mfma_f32_16x16x32_bf16 v[128:131], v[92:95], v[214:217], v[128:131]
	v_mfma_f32_16x16x32_bf16 v[116:119], v[84:87], v[230:233], v[116:119]
	v_mfma_f32_16x16x32_bf16 v[112:115], v[92:95], v[230:233], v[112:115]
	v_mfma_f32_16x16x32_bf16 v[100:103], v[84:87], v[238:241], v[100:103]
	v_mfma_f32_16x16x32_bf16 v[96:99], v[92:95], v[238:241], v[96:99]
	s_setprio 0
	s_barrier
	s_add_i32 m0, s16, 0x10000
	ds_read_b128 v[194:197], v204 offset:16384
	ds_read_b128 v[206:209], v242 offset:16384
	ds_read_b128 v[210:213], v204 offset:18432
	ds_read_b128 v[214:217], v242 offset:18432
	ds_read_b128 v[218:221], v204 offset:20480
	ds_read_b128 v[230:233], v242 offset:20480
	ds_read_b128 v[234:237], v204 offset:22528
	ds_read_b128 v[238:241], v242 offset:22528
	global_load_lds_dwordx4 v164, s[4:5]
	s_add_i32 m0, s16, 0x12000
	s_add_u32 s60, s4, 0x40000
	s_addc_u32 s61, s5, 0
	global_load_lds_dwordx4 v160, s[4:5]
	s_add_i32 m0, s16, 0x14000
	s_nop 0
	global_load_lds_dwordx4 v164, s[60:61]
	s_add_i32 m0, s16, 0x16000
	s_nop 0
	global_load_lds_dwordx4 v160, s[60:61]
	s_mov_b32 m0, s17
	s_nop 0
	global_load_lds_dwordx4 v166, s[24:25]
	s_mov_b32 m0, s18
	s_nop 0
	global_load_lds_dwordx4 v162, s[24:25]
	s_waitcnt vmcnt(8)
	s_waitcnt lgkmcnt(0)
	s_barrier
	s_setprio 1
	s_waitcnt lgkmcnt(0)
	v_mfma_f32_16x16x32_bf16 v[76:79], v[48:51], v[194:197], v[76:79]
	v_mfma_f32_16x16x32_bf16 v[72:75], v[56:59], v[194:197], v[72:75]
	v_mfma_f32_16x16x32_bf16 v[44:47], v[48:51], v[210:213], v[44:47]
	v_mfma_f32_16x16x32_bf16 v[40:43], v[56:59], v[210:213], v[40:43]
	v_mfma_f32_16x16x32_bf16 v[28:31], v[48:51], v[218:221], v[28:31]
	v_mfma_f32_16x16x32_bf16 v[24:27], v[56:59], v[218:221], v[24:27]
	v_mfma_f32_16x16x32_bf16 v[12:15], v[48:51], v[234:237], v[12:15]
	v_mfma_f32_16x16x32_bf16 v[8:11], v[56:59], v[234:237], v[8:11]
	v_mfma_f32_16x16x32_bf16 v[76:79], v[52:55], v[206:209], v[76:79]
	v_mfma_f32_16x16x32_bf16 v[72:75], v[60:63], v[206:209], v[72:75]
	v_mfma_f32_16x16x32_bf16 v[44:47], v[52:55], v[214:217], v[44:47]
	v_mfma_f32_16x16x32_bf16 v[40:43], v[60:63], v[214:217], v[40:43]
	v_mfma_f32_16x16x32_bf16 v[28:31], v[52:55], v[230:233], v[28:31]
	v_mfma_f32_16x16x32_bf16 v[24:27], v[60:63], v[230:233], v[24:27]
	v_mfma_f32_16x16x32_bf16 v[12:15], v[52:55], v[238:241], v[12:15]
	v_mfma_f32_16x16x32_bf16 v[8:11], v[60:63], v[238:241], v[8:11]
	s_setprio 0
	s_setprio 1
	v_mfma_f32_16x16x32_bf16 v[36:39], v[80:83], v[210:213], v[36:39]
	v_mfma_f32_16x16x32_bf16 v[32:35], v[88:91], v[210:213], v[32:35]
	v_mfma_f32_16x16x32_bf16 v[20:23], v[80:83], v[218:221], v[20:23]
	v_mfma_f32_16x16x32_bf16 v[16:19], v[88:91], v[218:221], v[16:19]
	v_mfma_f32_16x16x32_bf16 v[4:7], v[80:83], v[234:237], v[4:7]
	v_mfma_f32_16x16x32_bf16 v[0:3], v[88:91], v[234:237], v[0:3]
	v_mfma_f32_16x16x32_bf16 v[48:51], v[80:83], v[194:197], v[68:71]
	v_mfma_f32_16x16x32_bf16 v[52:55], v[88:91], v[194:197], v[64:67]
	v_mfma_f32_16x16x32_bf16 v[36:39], v[84:87], v[214:217], v[36:39]
	v_mfma_f32_16x16x32_bf16 v[32:35], v[92:95], v[214:217], v[32:35]
	v_mfma_f32_16x16x32_bf16 v[20:23], v[84:87], v[230:233], v[20:23]
	v_mfma_f32_16x16x32_bf16 v[16:19], v[92:95], v[230:233], v[16:19]
	v_mfma_f32_16x16x32_bf16 v[4:7], v[84:87], v[238:241], v[4:7]
	v_mfma_f32_16x16x32_bf16 v[0:3], v[92:95], v[238:241], v[0:3]
	v_mfma_f32_16x16x32_bf16 v[48:51], v[84:87], v[206:209], v[48:51]
	v_mfma_f32_16x16x32_bf16 v[52:55], v[92:95], v[206:209], v[52:55]
	s_setprio 0
	s_barrier
; #define PG8_STAGE(bufoff, gbase, voff) do { _Pragma("unroll") for (int _i = 0; _i < 2; ++_i) \
;         __builtin_amdgcn_global_load_lds((const unsigned*)((const char*)(gbase) + (voff)[_i]), (PG8_LAS unsigned*)(lds + (bufoff) + ldsw + _i * 8192), 16, 0, 0); } while (0)
; #define PG8_LDA(dst, b, h) do { _Pragma("unroll") for (int m = 0; m < 4; ++m) _Pragma("unroll") for (int k = 0; k < 2; ++k) dst[m][k] = *(const PG8_LAS bf16x8*)(lds + PG8_SA(b, h) + aoff + m * 2048 + k * 1024); } while (0)
; #define PG8_LDB(dst, b, h) do { _Pragma("unroll") for (int n = 0; n < 2; ++n) _Pragma("unroll") for (int k = 0; k < 2; ++k) dst[n][k] = *(const PG8_LAS bf16x8*)(lds + PG8_SB(b, h) + boff + n * 2048 + k * 1024); } while (0)
; #define PG8_MMA(ai, bj, At, Bt) do { __builtin_amdgcn_s_setprio(1); _Pragma("unroll") for (int m = 0; m < 4; ++m) _Pragma("unroll") for (int n = 0; n < 2; ++n) _Pragma("unroll") for (int k = 0; k < 2; ++k) \
;         acc[ai][bj][m][n] = __builtin_amdgcn_mfma_f32_16x16x32_bf16(Bt[n][k], At[m][k], acc[ai][bj][m][n], 0, 0, 0); __builtin_amdgcn_s_setprio(0); } while (0)
; #define PG8_WAIT_V(n) asm volatile("s_waitcnt vmcnt(" #n ")" ::: "memory")
; #define PG8_WAIT_L(n) asm volatile("s_waitcnt lgkmcnt(" #n ")" ::: "memory")
; #define PG8_BAR __builtin_amdgcn_s_barrier()
; #define PG8_SCHED __builtin_amdgcn_sched_barrier(0)
; template <class Epi, class Sched, bool ALIGN_EPI = false, bool SP2 = false>
; __device__ __forceinline__ void gemm_phase(PG8_LAS unsigned char* lds, const int tid, const Gemm g, const Sched& S, const Epi& E) {
;     ...
;             PG8_LDB(B0, 1, 0); PG8_LDB(B1, 1, 1); PG8_SCHED; PG8_LDA(At, 1, 0); PG8_STAGE(PG8_SA(0, 1), a2 + hstep, voffA);
;             PG8_WAIT_V(8); PG8_WAIT_L(0); PG8_BAR; PG8_MMA(0, 0, At, B0); PG8_MMA(0, 1, At, B1); PG8_BAR; PG8_SCHED;
;             PG8_LDA(At, 1, 1); PG8_STAGE(PG8_SB(1, 0), b3, voffB); PG8_STAGE(PG8_SB(1, 1), b3 + hstep, voffB); PG8_STAGE(PG8_SA(1, 0), a3, voffA);
;             PG8_WAIT_V(8); PG8_WAIT_L(0); PG8_BAR; PG8_MMA(1, 0, At, B0); PG8_MMA(1, 1, At, B1); PG8_BAR; PG8_SCHED;
	ds_read_b128 v[56:59], v243 offset:32768
	ds_read_b128 v[60:63], v244 offset:32768
	ds_read_b128 v[64:67], v243 offset:34816
	ds_read_b128 v[68:71], v244 offset:34816
	ds_read_b128 v[80:83], v243 offset:49152
	ds_read_b128 v[84:87], v244 offset:49152
	ds_read_b128 v[88:91], v243 offset:51200
	ds_read_b128 v[92:95], v244 offset:51200
	s_add_u32 s24, s24, 0x40000
	s_addc_u32 s25, s25, 0
	s_mov_b32 m0, s19
	ds_read_b128 v[194:197], v204 offset:32768
	ds_read_b128 v[206:209], v242 offset:32768
	ds_read_b128 v[210:213], v204 offset:34816
	ds_read_b128 v[214:217], v242 offset:34816
	ds_read_b128 v[218:221], v204 offset:36864
	ds_read_b128 v[230:233], v242 offset:36864
	ds_read_b128 v[234:237], v204 offset:38912
	ds_read_b128 v[238:241], v242 offset:38912
	global_load_lds_dwordx4 v166, s[24:25]
	s_mov_b32 m0, s20
	s_nop 0
	global_load_lds_dwordx4 v162, s[24:25]
	s_waitcnt vmcnt(8)
	s_waitcnt lgkmcnt(0)
	s_barrier
	s_setprio 1
	s_waitcnt lgkmcnt(0)
	v_mfma_f32_16x16x32_bf16 v[156:159], v[56:59], v[194:197], v[156:159]
	v_mfma_f32_16x16x32_bf16 v[152:155], v[64:67], v[194:197], v[152:155]
	v_mfma_f32_16x16x32_bf16 v[140:143], v[56:59], v[210:213], v[140:143]
	v_mfma_f32_16x16x32_bf16 v[136:139], v[64:67], v[210:213], v[136:139]
	v_mfma_f32_16x16x32_bf16 v[124:127], v[56:59], v[218:221], v[124:127]
	v_mfma_f32_16x16x32_bf16 v[120:123], v[64:67], v[218:221], v[120:123]
	v_mfma_f32_16x16x32_bf16 v[108:111], v[56:59], v[234:237], v[108:111]
	v_mfma_f32_16x16x32_bf16 v[104:107], v[64:67], v[234:237], v[104:107]
	v_mfma_f32_16x16x32_bf16 v[156:159], v[60:63], v[206:209], v[156:159]
	v_mfma_f32_16x16x32_bf16 v[152:155], v[68:71], v[206:209], v[152:155]
	v_mfma_f32_16x16x32_bf16 v[140:143], v[60:63], v[214:217], v[140:143]
	v_mfma_f32_16x16x32_bf16 v[136:139], v[68:71], v[214:217], v[136:139]
	v_mfma_f32_16x16x32_bf16 v[124:127], v[60:63], v[230:233], v[124:127]
	v_mfma_f32_16x16x32_bf16 v[120:123], v[68:71], v[230:233], v[120:123]
	v_mfma_f32_16x16x32_bf16 v[108:111], v[60:63], v[238:241], v[108:111]
	v_mfma_f32_16x16x32_bf16 v[104:107], v[68:71], v[238:241], v[104:107]
	s_setprio 0
	s_setprio 1
	v_mfma_f32_16x16x32_bf16 v[148:151], v[80:83], v[194:197], v[148:151]
	v_mfma_f32_16x16x32_bf16 v[144:147], v[88:91], v[194:197], v[144:147]
	v_mfma_f32_16x16x32_bf16 v[132:135], v[80:83], v[210:213], v[132:135]
	v_mfma_f32_16x16x32_bf16 v[128:131], v[88:91], v[210:213], v[128:131]
	v_mfma_f32_16x16x32_bf16 v[116:119], v[80:83], v[218:221], v[116:119]
	v_mfma_f32_16x16x32_bf16 v[112:115], v[88:91], v[218:221], v[112:115]
	v_mfma_f32_16x16x32_bf16 v[100:103], v[80:83], v[234:237], v[100:103]
	v_mfma_f32_16x16x32_bf16 v[96:99], v[88:91], v[234:237], v[96:99]
	v_mfma_f32_16x16x32_bf16 v[148:151], v[84:87], v[206:209], v[148:151]
	v_mfma_f32_16x16x32_bf16 v[144:147], v[92:95], v[206:209], v[144:147]
	v_mfma_f32_16x16x32_bf16 v[132:135], v[84:87], v[214:217], v[132:135]
	v_mfma_f32_16x16x32_bf16 v[128:131], v[92:95], v[214:217], v[128:131]
	v_mfma_f32_16x16x32_bf16 v[116:119], v[84:87], v[230:233], v[116:119]
	v_mfma_f32_16x16x32_bf16 v[112:115], v[92:95], v[230:233], v[112:115]
	v_mfma_f32_16x16x32_bf16 v[100:103], v[84:87], v[238:241], v[100:103]
	v_mfma_f32_16x16x32_bf16 v[96:99], v[92:95], v[238:241], v[96:99]
	s_setprio 0
	s_barrier
	s_add_u32 s94, s4, 0x80
	s_addc_u32 s95, s5, 0
	s_add_i32 m0, s16, 0x18000
	ds_read_b128 v[194:197], v204 offset:49152
	ds_read_b128 v[206:209], v242 offset:49152
	ds_read_b128 v[210:213], v204 offset:51200
	ds_read_b128 v[214:217], v242 offset:51200
	ds_read_b128 v[218:221], v204 offset:53248
	ds_read_b128 v[230:233], v242 offset:53248
	ds_read_b128 v[234:237], v204 offset:55296
	ds_read_b128 v[238:241], v242 offset:55296
	global_load_lds_dwordx4 v164, s[94:95]
	s_add_i32 m0, s16, 0x1a000
	s_add_u32 s4, s4, 0x40080
	s_addc_u32 s5, s5, 0
	global_load_lds_dwordx4 v160, s[94:95]
	s_add_i32 m0, s16, 0x1c000
	s_add_u32 s92, s24, 0xfffc0080
	s_addc_u32 s93, s25, -1
	global_load_lds_dwordx4 v164, s[4:5]
	s_add_i32 m0, s16, 0x1e000
	s_nop 0
	global_load_lds_dwordx4 v160, s[4:5]
	s_mov_b32 m0, s66
	s_nop 0
	global_load_lds_dwordx4 v166, s[92:93]
	s_mov_b32 m0, s67
	s_nop 0
	global_load_lds_dwordx4 v162, s[92:93]
	s_waitcnt vmcnt(8)
	s_waitcnt lgkmcnt(0)
	s_barrier
	s_setprio 1
	s_waitcnt lgkmcnt(0)
	v_mfma_f32_16x16x32_bf16 v[76:79], v[56:59], v[194:197], v[76:79]
	v_mfma_f32_16x16x32_bf16 v[72:75], v[64:67], v[194:197], v[72:75]
	v_mfma_f32_16x16x32_bf16 v[44:47], v[56:59], v[210:213], v[44:47]
	v_mfma_f32_16x16x32_bf16 v[40:43], v[64:67], v[210:213], v[40:43]
	v_mfma_f32_16x16x32_bf16 v[28:31], v[56:59], v[218:221], v[28:31]
	v_mfma_f32_16x16x32_bf16 v[24:27], v[64:67], v[218:221], v[24:27]
	v_mfma_f32_16x16x32_bf16 v[12:15], v[56:59], v[234:237], v[12:15]
	v_mfma_f32_16x16x32_bf16 v[8:11], v[64:67], v[234:237], v[8:11]
	v_mfma_f32_16x16x32_bf16 v[76:79], v[60:63], v[206:209], v[76:79]
	v_mfma_f32_16x16x32_bf16 v[72:75], v[68:71], v[206:209], v[72:75]
	v_mfma_f32_16x16x32_bf16 v[44:47], v[60:63], v[214:217], v[44:47]
	v_mfma_f32_16x16x32_bf16 v[40:43], v[68:71], v[214:217], v[40:43]
	v_mfma_f32_16x16x32_bf16 v[28:31], v[60:63], v[230:233], v[28:31]
	v_mfma_f32_16x16x32_bf16 v[24:27], v[68:71], v[230:233], v[24:27]
	v_mfma_f32_16x16x32_bf16 v[12:15], v[60:63], v[238:241], v[12:15]
	v_mfma_f32_16x16x32_bf16 v[8:11], v[68:71], v[238:241], v[8:11]
	s_setprio 0
	s_setprio 1
	v_mfma_f32_16x16x32_bf16 v[48:51], v[80:83], v[194:197], v[48:51]
	v_mfma_f32_16x16x32_bf16 v[68:71], v[84:87], v[206:209], v[48:51]
	v_mfma_f32_16x16x32_bf16 v[48:51], v[88:91], v[194:197], v[52:55]
	v_mfma_f32_16x16x32_bf16 v[36:39], v[80:83], v[210:213], v[36:39]
	v_mfma_f32_16x16x32_bf16 v[32:35], v[88:91], v[210:213], v[32:35]
	v_mfma_f32_16x16x32_bf16 v[20:23], v[80:83], v[218:221], v[20:23]
	v_mfma_f32_16x16x32_bf16 v[16:19], v[88:91], v[218:221], v[16:19]
	v_mfma_f32_16x16x32_bf16 v[4:7], v[80:83], v[234:237], v[4:7]
	v_mfma_f32_16x16x32_bf16 v[0:3], v[88:91], v[234:237], v[0:3]
	v_mfma_f32_16x16x32_bf16 v[64:67], v[92:95], v[206:209], v[48:51]
	v_mfma_f32_16x16x32_bf16 v[36:39], v[84:87], v[214:217], v[36:39]
	v_mfma_f32_16x16x32_bf16 v[32:35], v[92:95], v[214:217], v[32:35]
	v_mfma_f32_16x16x32_bf16 v[20:23], v[84:87], v[230:233], v[20:23]
	v_mfma_f32_16x16x32_bf16 v[16:19], v[92:95], v[230:233], v[16:19]
	v_mfma_f32_16x16x32_bf16 v[4:7], v[84:87], v[238:241], v[4:7]
	v_mfma_f32_16x16x32_bf16 v[0:3], v[92:95], v[238:241], v[0:3]
	s_setprio 0
	s_barrier
	s_add_i32 s41, s41, 2
	s_add_u32 s2, s2, 0x100
	s_addc_u32 s3, s3, 0
	s_add_u32 s38, s38, 0x100
	s_addc_u32 s39, s39, 0
	s_cmp_gt_u32 s41, 13
	s_cbranch_scc0 .LBB0_130
	s_and_b64 vcc, exec, s[50:51]
	s_cbranch_vccz .LBB0_133
	s_barrier

; template <class Epi, class Sched, bool ALIGN_EPI = false, bool SP2 = false>
; __device__ __forceinline__ void gemm_phase(PG8_LAS unsigned char* lds, const int tid, const Gemm g, const Sched& S, const Epi& E) {
;     const int wid = __builtin_amdgcn_readfirstlane(tid >> 6), lane = tid & 63, wr = wid >> 2, wc = wid & 3, fr = lane & 15, fq = lane >> 4;
;     const int K = g.K, nt = K / BK;
;     unsigned voffA[2], voffB[2];
; #pragma unroll
;     for (int i = 0; i < 2; ++i) { int R, C; stage_rc(tid * 16 + i * 8192, R, C); const int Rb = Epi::PERM ? ((R & ~31) + perm32(R & 31)) : R;
;         voffA[i] = (unsigned)(R * K + C) * 2u; voffB[i] = (unsigned)(Rb * K + C) * 2u; }
;     const size_t kstep = (size_t)(BK * 2);
;     const size_t hstep = (size_t)HALF * K * 2;
;     const size_t tstep = 2 * hstep;
;     const unsigned ldsw = (unsigned)wid * 1024u;
;     const int aoff = lds_byte(wr * 64 + fr, fq * 8), boff = lds_byte(wc * 32 + fr, fq * 8);
;     ...
;     if constexpr (SP2) {
;         PG8_STAGE(PG8_SB(0, 0), cB, voffB); PG8_STAGE(PG8_SB(0, 1), cB + hstep, voffB); PG8_STAGE(PG8_SA(0, 0), cA, voffA); PG8_STAGE(PG8_SA(0, 1), cA + hstep, voffA);
;         if (wr == 1) PG8_BAR;
; __global__ void __launch_bounds__(NTHR, 2) fwd_megakernel(Args a) {
;     ...
;             } else if (k == 1 || k == 7 || k == 5) {
;                 const int f = k == 7, sub = k == 1 ? 0 : (k == 5 ? 1 : 2);
;                 const bool last = (L == DEPTH - 1 && k == 7);
;                 const bf16_t* A = k == 5 ? YC : ACT; const bf16_t* Bt = k == 5 ? (const bf16_t*)(lw + LW_WOUT) : (const bf16_t*)(lw + LW_W2 + f * W2_BYTES);
;                 pg8::Gemm g{A, Bt, M, DM, k == 5 ? DM : FF, 0}; pg8::StaticOrder S; S.init(M, DM, gridDim.x, blockIdx.x);
;                 const int nn = L * 3 + sub + 1;
;                 const bool has = nn < DEPTH * 3; const int ni = has ? nn : 0;
;                 LAS pg8::EpiResid::P* pp = (LAS pg8::EpiResid::P*)(lds + MISC_OFF + 64);
;                 if (tid == 0) { pp->xinb = XB; pp->out = a.out; pp->outb = XB; pp->gate = lmod + sub * 3 * DM + 2 * DM; pp->rss = RSS + (size_t)ni * M;
;                     pp->gs = k == 5 ? 1.0f : 0.5f; pp->flags = (has ? 1 : 0) | (last ? 4 : 0); }
;                 __syncthreads();
;                 pg8::EpiResid E{pp};
;                 pg8::gemm_phase<pg8::EpiResid, pg8::StaticOrder, true, true>(lds, tid, g, S, E);
.LBB0_294:
	s_or_b64 exec, exec, s[2:3]
	v_readlane_b32 s2, v252, 32
	v_readlane_b32 s3, v252, 33
	s_andn2_b64 vcc, exec, s[2:3]
	v_readfirstlane_b32 s4, v184
	s_waitcnt lgkmcnt(0)
	s_barrier
	s_cbranch_vccnz .LBB0_413
	v_readlane_b32 s18, v251, 55
	v_readlane_b32 s19, v251, 56
	s_and_b64 s[2:3], s[18:19], exec
	s_movk_i32 s2, 0x400
	v_lshlrev_b32_e32 v3, 4, v184
	s_cselect_b32 s7, s2, 0xb00
	v_lshrrev_b32_e32 v234, 3, v182
	v_and_b32_e32 v235, 6, v234
	v_and_b32_e32 v236, 7, v182
	v_xor_b32_e32 v236, v236, v235
	v_lshlrev_b32_e32 v236, 4, v236
	v_mov_b32_e32 v237, s4
	v_lshrrev_b32_e32 v238, 6, v237
	v_lshl_add_u32 v239, v238, 3, v234
	v_mov_b32_e32 v240, s7
	v_lshlrev_b32_e32 v240, 1, v240
	v_mul_lo_u32 v241, v239, v240
	v_add_u32_e32 v242, v241, v236
	v_lshl_add_u32 v243, v240, 6, v242
	v_and_b32_e32 v241, 31, v239
	v_bfe_u32 v244, v241, 2, 2
	v_lshlrev_b32_e32 v244, 3, v244
	v_bfe_u32 v245, v241, 4, 1
	v_lshl_or_b32 v244, v245, 2, v244
	v_and_b32_e32 v245, 3, v241
	v_or_b32_e32 v244, v244, v245
	v_and_b32_e32 v245, 32, v239
	v_or_b32_e32 v244, v244, v245
	v_mul_lo_u32 v244, v244, v240
	v_add_u32_e32 v249, v244, v236
	v_lshl_add_u32 v254, v240, 6, v249
	v_and_b32_e32 v234, 15, v182
	v_lshrrev_b32_e32 v235, 4, v182
	v_and_b32_e32 v241, 6, v234
	v_xor_b32_e32 v235, v235, v241
	v_lshlrev_b32_e32 v235, 4, v235
	v_and_b32_e32 v241, 7, v234
	v_lshl_or_b32 v235, v241, 7, v235
	v_bfe_u32 v241, v234, 3, 1
	v_lshl_or_b32 v235, v241, 10, v235
	v_lshrrev_b32_e32 v241, 8, v237
	v_lshl_add_u32 v255, v241, 13, v235
	v_xor_b32_e32 v246, 64, v255
	v_bfe_u32 v241, v237, 6, 2
	v_lshl_add_u32 v233, v241, 12, v235
	v_xor_b32_e32 v248, 64, v233
	v_add_u32_e32 v247, 0x10000, v233
	v_add_u32_e32 v248, 0x10000, v248
	s_ashr_i32 s5, s4, 6
	v_add_u32_e32 v0, 0x2000, v3
	s_ashr_i32 s6, s4, 8
	s_lshl_b32 s12, s7, 8
	s_lshl_b32 s11, s7, 9
	s_lshl_b32 s15, s5, 10
	v_ashrrev_i32_e32 v1, 31, v0
	s_and_b64 s[2:3], s[18:19], exec
	v_lshrrev_b32_e32 v1, 22, v1
	v_readlane_b32 s2, v251, 57
	v_add_u32_e32 v1, v0, v1
	v_readlane_b32 s3, v251, 58
	v_readlane_b32 s10, v251, 50
	v_ashrrev_i32_e32 v1, 10, v1
	s_cselect_b32 s16, s3, s29
	s_cselect_b32 s17, s2, s28
	s_add_u32 s2, s10, 0x7b00000
	v_readlane_b32 s14, v251, 51
	v_mul_i32_i24_e32 v2, 0x400, v1
	s_addc_u32 s3, s14, 0
	v_sub_u32_e32 v0, v0, v2
	s_and_b64 s[0:1], s[0:1], exec
	v_lshrrev_b32_e32 v2, 4, v0
	s_cselect_b32 s0, 0x580000, 0
	v_bitop3_b32 v2, v2, v0, 32 bitop3:0x6c
	s_add_u32 s0, s10, s0
	v_ashrrev_i32_e32 v0, 31, v2
	s_addc_u32 s1, s14, 0
	v_lshrrev_b32_e32 v0, 26, v0
	s_add_u32 s10, s0, 0x7000000
	v_add_u32_e32 v4, v2, v0
	v_lshlrev_b32_e32 v5, 3, v1
	s_addc_u32 s14, s1, 0
	v_ashrrev_i32_e32 v0, 6, v4
	v_and_b32_e32 v5, -16, v5
	s_and_b64 s[0:1], s[18:19], exec
	v_add_u32_e32 v5, v0, v5
	v_and_b32_e32 v0, 3, v0
	s_mov_b32 s0, 0xffffe0
	v_lshrrev_b32_e32 v6, 2, v5
	v_lshlrev_b32_e32 v7, 1, v5
	v_and_or_b32 v0, v5, s0, v0
	v_and_b32_e32 v6, 4, v6
	v_and_b32_e32 v7, 24, v7
	v_or3_b32 v0, v0, v6, v7
	v_mul_u32_u24_e32 v6, s7, v0
	v_lshlrev_b32_e32 v0, 5, v1
	v_and_b32_e32 v1, 0xc0, v4
	v_sub_u32_e32 v1, v2, v1
	v_ashrrev_i16_sdwa v1, v223, sext(v1) dst_sel:DWORD dst_unused:UNUSED_PAD src0_sel:DWORD src1_sel:BYTE_0
	v_and_b32_e32 v0, 32, v0
	v_bfe_i32 v1, v1, 0, 16
	v_add_u32_e32 v4, v0, v1
	v_mul_lo_u32 v2, v5, s7
	v_mov_b32_e32 v186, v254
	v_mov_b32_e32 v188, v243
	v_bfe_i32 v4, v184, 27, 1
	v_lshrrev_b32_e32 v4, 22, v4
	v_add_u32_e32 v4, v3, v4
	v_and_b32_e32 v4, 0xfffffc00, v4
	v_sub_u32_e32 v3, v3, v4
	v_lshrrev_b32_e32 v4, 4, v3
	v_ashrrev_i32_e32 v6, 31, v184
	v_bitop3_b32 v4, v4, v3, 32 bitop3:0x6c
	v_lshrrev_b32_e32 v6, 26, v6
	v_ashrrev_i32_e32 v3, 31, v4
	v_add_u32_e32 v6, v184, v6
	v_lshrrev_b32_e32 v3, 26, v3
	v_ashrrev_i32_e32 v6, 6, v6
	v_add_u32_e32 v5, v4, v3
	v_lshlrev_b32_e32 v7, 3, v6
	v_ashrrev_i32_e32 v3, 6, v5
	v_and_b32_e32 v7, -16, v7
	v_add_u32_e32 v7, v3, v7
	v_and_b32_e32 v3, 3, v3
	v_and_or_b32 v3, v7, s0, v3
	v_lshrrev_b32_e32 v8, 2, v7
	v_lshlrev_b32_e32 v9, 1, v7
	v_readlane_b32 s0, v253, 51
	s_cselect_b32 s18, s3, s14
	s_cselect_b32 s19, s2, s10
	v_and_b32_e32 v8, 4, v8
	v_and_b32_e32 v9, 24, v9
	v_and_b32_e32 v5, 0xc0, v5
	s_mul_hi_i32 s2, s11, s0
	s_mul_i32 s3, s11, s0
	v_readlane_b32 s0, v253, 59
	v_or3_b32 v3, v3, v8, v9
	v_sub_u32_e32 v4, v4, v5
	v_readlane_b32 s1, v253, 60
	s_mov_b32 s10, s0
	v_mul_u32_u24_e32 v8, s7, v3
	v_lshlrev_b32_e32 v3, 5, v6
	v_ashrrev_i16_sdwa v4, v223, sext(v4) dst_sel:DWORD dst_unused:UNUSED_PAD src0_sel:DWORD src1_sel:BYTE_0
	s_mul_i32 s1, s11, s10
	v_and_b32_e32 v3, 32, v3
	v_bfe_i32 v4, v4, 0, 16
	s_mul_hi_i32 s0, s11, s0
	s_add_u32 s24, s19, s1
	v_add_u32_e32 v6, v3, v4
	s_addc_u32 s25, s18, s0
	s_add_i32 s20, s15, 0
	v_mov_b32_e32 v168, v249
	s_add_i32 m0, s20, 0x10000
	v_mul_lo_u32 v5, v7, s7
	global_load_lds_dwordx4 v168, s[24:25]
	s_add_i32 m0, s20, 0x12000
	s_add_u32 s0, s24, s12
	global_load_lds_dwordx4 v186, s[24:25]
	s_addc_u32 s1, s25, 0
	s_add_i32 m0, s20, 0x14000
	v_mov_b32_e32 v190, v242
	global_load_lds_dwordx4 v168, s[0:1]
	s_add_i32 m0, s20, 0x16000
	s_add_u32 s26, s17, s3
	s_addc_u32 s27, s16, s2
	s_add_i32 s21, s20, 0x2000
	global_load_lds_dwordx4 v186, s[0:1]
	s_mov_b32 m0, s20
	s_add_u32 s2, s26, s12
	global_load_lds_dwordx4 v190, s[26:27]
	s_mov_b32 m0, s21
	s_addc_u32 s3, s27, 0
	s_add_i32 s22, s20, 0x4000
	global_load_lds_dwordx4 v188, s[26:27]
	s_mov_b32 m0, s22
	s_add_i32 s23, s20, 0x6000
	global_load_lds_dwordx4 v190, s[2:3]
	s_mov_b32 m0, s23
	s_cmp_eq_u32 s6, 1
	global_load_lds_dwordx4 v188, s[2:3]
	s_mov_b64 s[56:57], s[28:29]
	s_cselect_b64 s[2:3], -1, 0
	s_cmp_lg_u32 s6, 1
	s_cbranch_scc1 .LBB0_297
	s_barrier
; #define PG8_STAGE(bufoff, gbase, voff) do { _Pragma("unroll") for (int _i = 0; _i < 2; ++_i) \
;         __builtin_amdgcn_global_load_lds((const unsigned*)((const char*)(gbase) + (voff)[_i]), (PG8_LAS unsigned*)(lds + (bufoff) + ldsw + _i * 8192), 16, 0, 0); } while (0)
; #define PG8_WAIT_V(n) asm volatile("s_waitcnt vmcnt(" #n ")" ::: "memory")
; #define PG8_BAR __builtin_amdgcn_s_barrier()
; template <class Epi, class Sched, bool ALIGN_EPI = false, bool SP2 = false>
; __device__ __forceinline__ void gemm_phase(PG8_LAS unsigned char* lds, const int tid, const Gemm g, const Sched& S, const Epi& E) {
;     ...
;         if (wr == 1) PG8_BAR;
;         PG8_WAIT_V(2); PG8_BAR;
;         PG8_STAGE(PG8_SB(1, 0), cB + kstep, voffB); PG8_STAGE(PG8_SA(1, 0), cA + kstep, voffA); PG8_STAGE(PG8_SB(1, 1), cB + hstep + kstep, voffB);
;         PG8_WAIT_V(6); PG8_BAR;
.LBB0_297:
	v_lshl_add_u64 v[6:7], s[24:25], 0, v[168:169]
	v_mov_b32_e32 v187, v169
	v_lshl_add_u64 v[8:9], s[24:25], 0, v[186:187]
	v_mov_b32_e32 v191, v169
	s_add_i32 m0, s20, 0x18000
	v_lshl_add_u64 v[6:7], v[6:7], 0, s[36:37]
	v_lshl_add_u64 v[14:15], s[26:27], 0, v[190:191]
	v_mov_b32_e32 v189, v169
	s_waitcnt vmcnt(2)
	s_barrier
	global_load_lds_dwordx4 v[6:7], off
	v_lshl_add_u64 v[6:7], v[8:9], 0, s[36:37]
	s_add_i32 m0, s20, 0x1a000
	s_add_i32 s45, s20, 0x8000
	v_lshl_add_u64 v[16:17], s[26:27], 0, v[188:189]
	global_load_lds_dwordx4 v[6:7], off
	v_lshl_add_u64 v[6:7], v[14:15], 0, s[36:37]
	s_mov_b32 m0, s45
	s_add_i32 s46, s20, 0xa000
	v_lshl_add_u64 v[10:11], s[0:1], 0, v[168:169]
	global_load_lds_dwordx4 v[6:7], off
	v_lshl_add_u64 v[6:7], v[16:17], 0, s[36:37]
	s_mov_b32 m0, s46
	v_lshl_add_u64 v[12:13], s[0:1], 0, v[186:187]
	global_load_lds_dwordx4 v[6:7], off
	s_add_i32 m0, s20, 0x1c000
	v_lshl_add_u64 v[6:7], v[10:11], 0, s[36:37]
	global_load_lds_dwordx4 v[6:7], off
	v_lshl_add_u64 v[6:7], v[12:13], 0, s[36:37]
	s_add_i32 m0, s20, 0x1e000
	v_bfe_u32 v18, v182, 4, 2
	global_load_lds_dwordx4 v[6:7], off
	v_and_b32_e32 v19, 15, v182
	v_lshlrev_b32_e32 v20, 4, v18
	v_lshl_or_b32 v183, s6, 6, v19
	v_lshl_or_b32 v19, v19, 6, v20
	v_lshlrev_b32_e32 v20, 2, v182
	s_lshl_b32 s0, s6, 13
	v_and_b32_e32 v20, 32, v20
	v_bitop3_b32 v21, v19, s0, v20 bitop3:0xde
	s_lshl_b32 s0, s5, 5
	v_xor_b32_e32 v6, 16, v224
	s_lshr_b32 s44, s7, 6
	s_and_b32 s5, s0, 0x60
	v_cmp_lt_i32_e32 vcc, v6, v226
	s_lshl_b32 s0, s5, 7
	s_waitcnt vmcnt(6)
	s_add_i32 s47, s44, -2
	v_cndmask_b32_e32 v6, v224, v6, vcc
	v_cmp_lt_i32_e32 vcc, v225, v226
	v_add_u32_e32 v3, v5, v3
	v_add_u32_e32 v0, v2, v0
	s_cmpk_lt_u32 s4, 0x100
	v_lshlrev_b32_e32 v229, 2, v6
	v_cndmask_b32_e32 v6, v224, v225, vcc
	v_add_lshl_u32 v4, v3, v4, 1
	v_mov_b32_e32 v5, v169
	v_add_lshl_u32 v0, v0, v1, 1
	v_mov_b32_e32 v1, v169
	v_mov_b32_e32 v185, v233
	s_cselect_b64 s[6:7], -1, 0
	s_mov_b32 s48, 0
	v_cmp_eq_u32_e64 s[0:1], 0, v18
	v_lshlrev_b32_e32 v230, 2, v6
	v_lshl_or_b32 v231, v18, 3, s5
	v_lshl_add_u64 v[192:193], s[12:13], 0, v[4:5]
	v_lshl_add_u64 v[194:195], s[12:13], 0, v[0:1]
	v_mov_b32_e32 v232, v255
	v_readlane_b32 s41, v253, 58
	v_readlane_b32 s40, v253, 51
	s_barrier
	s_branch .LBB0_300

; #define PG8_STAGE(bufoff, gbase, voff) do { _Pragma("unroll") for (int _i = 0; _i < 2; ++_i) \
;         __builtin_amdgcn_global_load_lds((const unsigned*)((const char*)(gbase) + (voff)[_i]), (PG8_LAS unsigned*)(lds + (bufoff) + ldsw + _i * 8192), 16, 0, 0); } while (0)
; #define PG8_LDA(dst, b, h) do { _Pragma("unroll") for (int m = 0; m < 4; ++m) _Pragma("unroll") for (int k = 0; k < 2; ++k) dst[m][k] = *(const PG8_LAS bf16x8*)(lds + PG8_SA(b, h) + aoff + m * 2048 + k * 1024); } while (0)
; #define PG8_LDB(dst, b, h) do { _Pragma("unroll") for (int n = 0; n < 2; ++n) _Pragma("unroll") for (int k = 0; k < 2; ++k) dst[n][k] = *(const PG8_LAS bf16x8*)(lds + PG8_SB(b, h) + boff + n * 2048 + k * 1024); } while (0)
; #define PG8_MMA(ai, bj, At, Bt) do { __builtin_amdgcn_s_setprio(1); _Pragma("unroll") for (int m = 0; m < 4; ++m) _Pragma("unroll") for (int n = 0; n < 2; ++n) _Pragma("unroll") for (int k = 0; k < 2; ++k) \
;         acc[ai][bj][m][n] = __builtin_amdgcn_mfma_f32_16x16x32_bf16(Bt[n][k], At[m][k], acc[ai][bj][m][n], 0, 0, 0); __builtin_amdgcn_s_setprio(0); } while (0)
; #define PG8_WAIT_V(n) asm volatile("s_waitcnt vmcnt(" #n ")" ::: "memory")
; #define PG8_WAIT_L(n) asm volatile("s_waitcnt lgkmcnt(" #n ")" ::: "memory")
; #define PG8_BAR __builtin_amdgcn_s_barrier()
; #define PG8_SCHED __builtin_amdgcn_sched_barrier(0)
; template <class Epi, class Sched, bool ALIGN_EPI = false, bool SP2 = false>
; __device__ __forceinline__ void gemm_phase(PG8_LAS unsigned char* lds, const int tid, const Gemm g, const Sched& S, const Epi& E) {
;     ...
;             PG8_LDB(B0, 0, 0); PG8_LDB(B1, 0, 1); PG8_SCHED; PG8_LDA(At, 0, 0); PG8_STAGE(PG8_SA(1, 1), a1 + hstep, voffA);
;             PG8_WAIT_V(8); PG8_WAIT_L(0); PG8_BAR; PG8_MMA(0, 0, At, B0); PG8_MMA(0, 1, At, B1); PG8_BAR; PG8_SCHED;
;             PG8_LDA(At, 0, 1); PG8_STAGE(PG8_SB(0, 0), b2, voffB); PG8_STAGE(PG8_SB(0, 1), b2 + hstep, voffB); PG8_STAGE(PG8_SA(0, 0), a2, voffA);
;             PG8_WAIT_V(8); PG8_WAIT_L(0); PG8_BAR; PG8_MMA(1, 0, At, B0); PG8_MMA(1, 1, At, B1); PG8_BAR; PG8_SCHED;
.LBB0_311:
	s_add_i32 s51, s14, 2
	s_add_u32 s10, s38, 0x80
	s_addc_u32 s24, s39, 0
	s_cmp_eq_u32 s47, s14
	s_cselect_b32 s25, s29, s24
	s_cselect_b32 s24, s28, s10
	s_cselect_b32 s53, s43, s27
	s_cselect_b32 s52, s42, s26
	s_add_u32 s92, s38, s12
	s_addc_u32 s93, s39, 0
	ds_read_b128 v[72:75], v247
	ds_read_b128 v[76:79], v248
	ds_read_b128 v[136:139], v247 offset:2048
	ds_read_b128 v[140:143], v248 offset:2048
	ds_read_b128 v[144:147], v247 offset:16384
	ds_read_b128 v[148:151], v248 offset:16384
	ds_read_b128 v[152:155], v247 offset:18432
	ds_read_b128 v[156:159], v248 offset:18432
	s_add_i32 m0, s20, 0xc000
	ds_read_b128 v[160:163], v232
	ds_read_b128 v[164:167], v246
	ds_read_b128 v[196:199], v232 offset:2048
	ds_read_b128 v[200:203], v246 offset:2048
	ds_read_b128 v[204:207], v232 offset:4096
	ds_read_b128 v[208:211], v246 offset:4096
	ds_read_b128 v[212:215], v232 offset:6144
	ds_read_b128 v[216:219], v246 offset:6144
	global_load_lds_dwordx4 v190, s[92:93]
	s_add_i32 m0, s20, 0xe000
	s_nop 0
	global_load_lds_dwordx4 v188, s[92:93]
	s_waitcnt vmcnt(8)
	s_waitcnt lgkmcnt(0)
	s_barrier
	s_setprio 1
	s_waitcnt lgkmcnt(0)
	v_mfma_f32_16x16x32_bf16 v[132:135], v[72:75], v[160:163], v[132:135]
	v_mfma_f32_16x16x32_bf16 v[128:131], v[136:139], v[160:163], v[128:131]
	v_mfma_f32_16x16x32_bf16 v[116:119], v[72:75], v[196:199], v[116:119]
	v_mfma_f32_16x16x32_bf16 v[112:115], v[136:139], v[196:199], v[112:115]
	v_mfma_f32_16x16x32_bf16 v[100:103], v[72:75], v[204:207], v[100:103]
	v_mfma_f32_16x16x32_bf16 v[96:99], v[136:139], v[204:207], v[96:99]
	v_mfma_f32_16x16x32_bf16 v[84:87], v[72:75], v[212:215], v[84:87]
	v_mfma_f32_16x16x32_bf16 v[80:83], v[136:139], v[212:215], v[80:83]
	v_mfma_f32_16x16x32_bf16 v[132:135], v[76:79], v[164:167], v[132:135]
	v_mfma_f32_16x16x32_bf16 v[128:131], v[140:143], v[164:167], v[128:131]
	v_mfma_f32_16x16x32_bf16 v[116:119], v[76:79], v[200:203], v[116:119]
	v_mfma_f32_16x16x32_bf16 v[112:115], v[140:143], v[200:203], v[112:115]
	v_mfma_f32_16x16x32_bf16 v[100:103], v[76:79], v[208:211], v[100:103]
	v_mfma_f32_16x16x32_bf16 v[96:99], v[140:143], v[208:211], v[96:99]
	v_mfma_f32_16x16x32_bf16 v[84:87], v[76:79], v[216:219], v[84:87]
	v_mfma_f32_16x16x32_bf16 v[80:83], v[140:143], v[216:219], v[80:83]
	s_setprio 0
	s_setprio 1
	v_mfma_f32_16x16x32_bf16 v[124:127], v[144:147], v[160:163], v[124:127]
	v_mfma_f32_16x16x32_bf16 v[120:123], v[152:155], v[160:163], v[120:123]
	v_mfma_f32_16x16x32_bf16 v[108:111], v[144:147], v[196:199], v[108:111]
	v_mfma_f32_16x16x32_bf16 v[104:107], v[152:155], v[196:199], v[104:107]
	v_mfma_f32_16x16x32_bf16 v[92:95], v[144:147], v[204:207], v[92:95]
	v_mfma_f32_16x16x32_bf16 v[88:91], v[152:155], v[204:207], v[88:91]
	v_mfma_f32_16x16x32_bf16 v[68:71], v[144:147], v[212:215], v[68:71]
	v_mfma_f32_16x16x32_bf16 v[64:67], v[152:155], v[212:215], v[64:67]
	v_mfma_f32_16x16x32_bf16 v[124:127], v[148:151], v[164:167], v[124:127]
	v_mfma_f32_16x16x32_bf16 v[120:123], v[156:159], v[164:167], v[120:123]
	v_mfma_f32_16x16x32_bf16 v[108:111], v[148:151], v[200:203], v[108:111]
	v_mfma_f32_16x16x32_bf16 v[104:107], v[156:159], v[200:203], v[104:107]
	v_mfma_f32_16x16x32_bf16 v[92:95], v[148:151], v[208:211], v[92:95]
	v_mfma_f32_16x16x32_bf16 v[88:91], v[156:159], v[208:211], v[88:91]
	v_mfma_f32_16x16x32_bf16 v[68:71], v[148:151], v[216:219], v[68:71]
	v_mfma_f32_16x16x32_bf16 v[64:67], v[156:159], v[216:219], v[64:67]
	s_setprio 0
	s_barrier
	s_add_i32 m0, s15, 0x10000
	ds_read_b128 v[160:163], v232 offset:16384
	ds_read_b128 v[164:167], v246 offset:16384
	ds_read_b128 v[196:199], v232 offset:18432
	ds_read_b128 v[200:203], v246 offset:18432
	ds_read_b128 v[204:207], v232 offset:20480
	ds_read_b128 v[208:211], v246 offset:20480
	ds_read_b128 v[212:215], v232 offset:22528
	ds_read_b128 v[216:219], v246 offset:22528
	global_load_lds_dwordx4 v168, s[52:53]
	s_add_i32 m0, s15, 0x12000
	s_add_u32 s94, s52, 0x80
	s_addc_u32 s95, s53, 0
	global_load_lds_dwordx4 v186, s[52:53]
	s_add_u32 s52, s52, s12
	s_addc_u32 s53, s53, 0
	s_add_i32 m0, s15, 0x14000
	s_add_u32 s98, s24, 0x80
	s_addc_u32 s99, s25, 0
	global_load_lds_dwordx4 v168, s[52:53]
	s_add_i32 m0, s15, 0x16000
	s_nop 0
	global_load_lds_dwordx4 v186, s[52:53]
	s_mov_b32 m0, s20
	s_nop 0
	global_load_lds_dwordx4 v190, s[24:25]
	s_mov_b32 m0, s21
	s_nop 0
	global_load_lds_dwordx4 v188, s[24:25]
	s_waitcnt vmcnt(8)
	s_waitcnt lgkmcnt(0)
	s_barrier
	s_setprio 1
	s_waitcnt lgkmcnt(0)
	v_mfma_f32_16x16x32_bf16 v[60:63], v[72:75], v[160:163], v[60:63]
	v_mfma_f32_16x16x32_bf16 v[56:59], v[136:139], v[160:163], v[56:59]
	v_mfma_f32_16x16x32_bf16 v[44:47], v[72:75], v[196:199], v[44:47]
	v_mfma_f32_16x16x32_bf16 v[40:43], v[136:139], v[196:199], v[40:43]
	v_mfma_f32_16x16x32_bf16 v[28:31], v[72:75], v[204:207], v[28:31]
	v_mfma_f32_16x16x32_bf16 v[24:27], v[136:139], v[204:207], v[24:27]
	v_mfma_f32_16x16x32_bf16 v[12:15], v[72:75], v[212:215], v[12:15]
	v_mfma_f32_16x16x32_bf16 v[8:11], v[136:139], v[212:215], v[8:11]
	v_mfma_f32_16x16x32_bf16 v[60:63], v[76:79], v[164:167], v[60:63]
	v_mfma_f32_16x16x32_bf16 v[56:59], v[140:143], v[164:167], v[56:59]
	v_mfma_f32_16x16x32_bf16 v[44:47], v[76:79], v[200:203], v[44:47]
	v_mfma_f32_16x16x32_bf16 v[40:43], v[140:143], v[200:203], v[40:43]
	v_mfma_f32_16x16x32_bf16 v[28:31], v[76:79], v[208:211], v[28:31]
	v_mfma_f32_16x16x32_bf16 v[24:27], v[140:143], v[208:211], v[24:27]
	v_mfma_f32_16x16x32_bf16 v[12:15], v[76:79], v[216:219], v[12:15]
	v_mfma_f32_16x16x32_bf16 v[8:11], v[140:143], v[216:219], v[8:11]
	s_setprio 0
	s_setprio 1
	v_mfma_f32_16x16x32_bf16 v[52:55], v[144:147], v[160:163], v[52:55]
	v_mfma_f32_16x16x32_bf16 v[48:51], v[152:155], v[160:163], v[48:51]
	v_mfma_f32_16x16x32_bf16 v[36:39], v[144:147], v[196:199], v[36:39]
	v_mfma_f32_16x16x32_bf16 v[32:35], v[152:155], v[196:199], v[32:35]
	v_mfma_f32_16x16x32_bf16 v[20:23], v[144:147], v[204:207], v[20:23]
	v_mfma_f32_16x16x32_bf16 v[16:19], v[152:155], v[204:207], v[16:19]
	v_mfma_f32_16x16x32_bf16 v[4:7], v[144:147], v[212:215], v[4:7]
	v_mfma_f32_16x16x32_bf16 v[0:3], v[152:155], v[212:215], v[0:3]
	v_mfma_f32_16x16x32_bf16 v[52:55], v[148:151], v[164:167], v[52:55]
	v_mfma_f32_16x16x32_bf16 v[48:51], v[156:159], v[164:167], v[48:51]
	v_mfma_f32_16x16x32_bf16 v[36:39], v[148:151], v[200:203], v[36:39]
	v_mfma_f32_16x16x32_bf16 v[32:35], v[156:159], v[200:203], v[32:35]
	v_mfma_f32_16x16x32_bf16 v[20:23], v[148:151], v[208:211], v[20:23]
	v_mfma_f32_16x16x32_bf16 v[16:19], v[156:159], v[208:211], v[16:19]
	v_mfma_f32_16x16x32_bf16 v[4:7], v[148:151], v[216:219], v[4:7]
	v_mfma_f32_16x16x32_bf16 v[0:3], v[156:159], v[216:219], v[0:3]
	s_setprio 0
	s_barrier
; #define PG8_STAGE(bufoff, gbase, voff) do { _Pragma("unroll") for (int _i = 0; _i < 2; ++_i) \
;         __builtin_amdgcn_global_load_lds((const unsigned*)((const char*)(gbase) + (voff)[_i]), (PG8_LAS unsigned*)(lds + (bufoff) + ldsw + _i * 8192), 16, 0, 0); } while (0)
; #define PG8_LDA(dst, b, h) do { _Pragma("unroll") for (int m = 0; m < 4; ++m) _Pragma("unroll") for (int k = 0; k < 2; ++k) dst[m][k] = *(const PG8_LAS bf16x8*)(lds + PG8_SA(b, h) + aoff + m * 2048 + k * 1024); } while (0)
; #define PG8_LDB(dst, b, h) do { _Pragma("unroll") for (int n = 0; n < 2; ++n) _Pragma("unroll") for (int k = 0; k < 2; ++k) dst[n][k] = *(const PG8_LAS bf16x8*)(lds + PG8_SB(b, h) + boff + n * 2048 + k * 1024); } while (0)
; #define PG8_MMA(ai, bj, At, Bt) do { __builtin_amdgcn_s_setprio(1); _Pragma("unroll") for (int m = 0; m < 4; ++m) _Pragma("unroll") for (int n = 0; n < 2; ++n) _Pragma("unroll") for (int k = 0; k < 2; ++k) \
;         acc[ai][bj][m][n] = __builtin_amdgcn_mfma_f32_16x16x32_bf16(Bt[n][k], At[m][k], acc[ai][bj][m][n], 0, 0, 0); __builtin_amdgcn_s_setprio(0); } while (0)
; #define PG8_WAIT_V(n) asm volatile("s_waitcnt vmcnt(" #n ")" ::: "memory")
; #define PG8_WAIT_L(n) asm volatile("s_waitcnt lgkmcnt(" #n ")" ::: "memory")
; #define PG8_BAR __builtin_amdgcn_s_barrier()
; #define PG8_SCHED __builtin_amdgcn_sched_barrier(0)
; template <class Epi, class Sched, bool ALIGN_EPI = false, bool SP2 = false>
; __device__ __forceinline__ void gemm_phase(PG8_LAS unsigned char* lds, const int tid, const Gemm g, const Sched& S, const Epi& E) {
;     ...
;             PG8_LDB(B0, 1, 0); PG8_LDB(B1, 1, 1); PG8_SCHED; PG8_LDA(At, 1, 0); PG8_STAGE(PG8_SA(0, 1), a2 + hstep, voffA);
;             PG8_WAIT_V(8); PG8_WAIT_L(0); PG8_BAR; PG8_MMA(0, 0, At, B0); PG8_MMA(0, 1, At, B1); PG8_BAR; PG8_SCHED;
;             PG8_LDA(At, 1, 1); PG8_STAGE(PG8_SB(1, 0), b3, voffB); PG8_STAGE(PG8_SB(1, 1), b3 + hstep, voffB); PG8_STAGE(PG8_SA(1, 0), a3, voffA);
;             PG8_WAIT_V(8); PG8_WAIT_L(0); PG8_BAR; PG8_MMA(1, 0, At, B0); PG8_MMA(1, 1, At, B1); PG8_BAR; PG8_SCHED;
	ds_read_b128 v[72:75], v247 offset:32768
	ds_read_b128 v[76:79], v248 offset:32768
	ds_read_b128 v[136:139], v247 offset:34816
	ds_read_b128 v[140:143], v248 offset:34816
	ds_read_b128 v[144:147], v247 offset:49152
	ds_read_b128 v[148:151], v248 offset:49152
	ds_read_b128 v[152:155], v247 offset:51200
	ds_read_b128 v[156:159], v248 offset:51200
	s_add_u32 s24, s24, s12
	s_addc_u32 s25, s25, 0
	s_mov_b32 m0, s22
	ds_read_b128 v[160:163], v232 offset:32768
	ds_read_b128 v[164:167], v246 offset:32768
	ds_read_b128 v[196:199], v232 offset:34816
	ds_read_b128 v[200:203], v246 offset:34816
	ds_read_b128 v[204:207], v232 offset:36864
	ds_read_b128 v[208:211], v246 offset:36864
	ds_read_b128 v[212:215], v232 offset:38912
	ds_read_b128 v[216:219], v246 offset:38912
	global_load_lds_dwordx4 v190, s[24:25]
	s_mov_b32 m0, s23
	s_nop 0
	global_load_lds_dwordx4 v188, s[24:25]
	s_waitcnt vmcnt(8)
	s_waitcnt lgkmcnt(0)
	s_barrier
	s_setprio 1
	s_waitcnt lgkmcnt(0)
	v_mfma_f32_16x16x32_bf16 v[132:135], v[72:75], v[160:163], v[132:135]
	v_mfma_f32_16x16x32_bf16 v[128:131], v[136:139], v[160:163], v[128:131]
	v_mfma_f32_16x16x32_bf16 v[116:119], v[72:75], v[196:199], v[116:119]
	v_mfma_f32_16x16x32_bf16 v[112:115], v[136:139], v[196:199], v[112:115]
	v_mfma_f32_16x16x32_bf16 v[100:103], v[72:75], v[204:207], v[100:103]
	v_mfma_f32_16x16x32_bf16 v[96:99], v[136:139], v[204:207], v[96:99]
	v_mfma_f32_16x16x32_bf16 v[84:87], v[72:75], v[212:215], v[84:87]
	v_mfma_f32_16x16x32_bf16 v[80:83], v[136:139], v[212:215], v[80:83]
	v_mfma_f32_16x16x32_bf16 v[132:135], v[76:79], v[164:167], v[132:135]
	v_mfma_f32_16x16x32_bf16 v[128:131], v[140:143], v[164:167], v[128:131]
	v_mfma_f32_16x16x32_bf16 v[116:119], v[76:79], v[200:203], v[116:119]
	v_mfma_f32_16x16x32_bf16 v[112:115], v[140:143], v[200:203], v[112:115]
	v_mfma_f32_16x16x32_bf16 v[100:103], v[76:79], v[208:211], v[100:103]
	v_mfma_f32_16x16x32_bf16 v[96:99], v[140:143], v[208:211], v[96:99]
	v_mfma_f32_16x16x32_bf16 v[84:87], v[76:79], v[216:219], v[84:87]
	v_mfma_f32_16x16x32_bf16 v[80:83], v[140:143], v[216:219], v[80:83]
	s_setprio 0
	s_setprio 1
	v_mfma_f32_16x16x32_bf16 v[124:127], v[144:147], v[160:163], v[124:127]
	v_mfma_f32_16x16x32_bf16 v[120:123], v[152:155], v[160:163], v[120:123]
	v_mfma_f32_16x16x32_bf16 v[108:111], v[144:147], v[196:199], v[108:111]
	v_mfma_f32_16x16x32_bf16 v[104:107], v[152:155], v[196:199], v[104:107]
	v_mfma_f32_16x16x32_bf16 v[92:95], v[144:147], v[204:207], v[92:95]
	v_mfma_f32_16x16x32_bf16 v[88:91], v[152:155], v[204:207], v[88:91]
	v_mfma_f32_16x16x32_bf16 v[68:71], v[144:147], v[212:215], v[68:71]
	v_mfma_f32_16x16x32_bf16 v[64:67], v[152:155], v[212:215], v[64:67]
	v_mfma_f32_16x16x32_bf16 v[124:127], v[148:151], v[164:167], v[124:127]
	v_mfma_f32_16x16x32_bf16 v[120:123], v[156:159], v[164:167], v[120:123]
	v_mfma_f32_16x16x32_bf16 v[108:111], v[148:151], v[200:203], v[108:111]
	v_mfma_f32_16x16x32_bf16 v[104:107], v[156:159], v[200:203], v[104:107]
	v_mfma_f32_16x16x32_bf16 v[92:95], v[148:151], v[208:211], v[92:95]
	v_mfma_f32_16x16x32_bf16 v[88:91], v[156:159], v[208:211], v[88:91]
	v_mfma_f32_16x16x32_bf16 v[68:71], v[148:151], v[216:219], v[68:71]
	v_mfma_f32_16x16x32_bf16 v[64:67], v[156:159], v[216:219], v[64:67]
	s_setprio 0
	s_barrier
	s_add_u32 s96, s52, 0x80
	s_addc_u32 s97, s53, 0
	s_add_i32 m0, s15, 0x18000
	ds_read_b128 v[160:163], v232 offset:49152
	ds_read_b128 v[164:167], v246 offset:49152
	ds_read_b128 v[196:199], v232 offset:51200
	ds_read_b128 v[200:203], v246 offset:51200
	ds_read_b128 v[204:207], v232 offset:53248
	ds_read_b128 v[208:211], v246 offset:53248
	ds_read_b128 v[212:215], v232 offset:55296
	ds_read_b128 v[216:219], v246 offset:55296
	global_load_lds_dwordx4 v168, s[94:95]
	s_add_i32 m0, s15, 0x1a000
	s_nop 0
	global_load_lds_dwordx4 v186, s[94:95]
	s_add_i32 m0, s15, 0x1c000
	s_nop 0
	global_load_lds_dwordx4 v168, s[96:97]
	s_add_i32 m0, s15, 0x1e000
	s_nop 0
	global_load_lds_dwordx4 v186, s[96:97]
	s_mov_b32 m0, s45
	s_nop 0
	global_load_lds_dwordx4 v190, s[98:99]
	s_mov_b32 m0, s46
	s_nop 0
	global_load_lds_dwordx4 v188, s[98:99]
	s_waitcnt vmcnt(8)
	s_waitcnt lgkmcnt(0)
	s_barrier
	s_setprio 1
	s_waitcnt lgkmcnt(0)
	v_mfma_f32_16x16x32_bf16 v[60:63], v[72:75], v[160:163], v[60:63]
	v_mfma_f32_16x16x32_bf16 v[56:59], v[136:139], v[160:163], v[56:59]
	v_mfma_f32_16x16x32_bf16 v[44:47], v[72:75], v[196:199], v[44:47]
	v_mfma_f32_16x16x32_bf16 v[40:43], v[136:139], v[196:199], v[40:43]
	v_mfma_f32_16x16x32_bf16 v[28:31], v[72:75], v[204:207], v[28:31]
	v_mfma_f32_16x16x32_bf16 v[24:27], v[136:139], v[204:207], v[24:27]
	v_mfma_f32_16x16x32_bf16 v[12:15], v[72:75], v[212:215], v[12:15]
	v_mfma_f32_16x16x32_bf16 v[8:11], v[136:139], v[212:215], v[8:11]
	v_mfma_f32_16x16x32_bf16 v[60:63], v[76:79], v[164:167], v[60:63]
	v_mfma_f32_16x16x32_bf16 v[56:59], v[140:143], v[164:167], v[56:59]
	v_mfma_f32_16x16x32_bf16 v[44:47], v[76:79], v[200:203], v[44:47]
	v_mfma_f32_16x16x32_bf16 v[40:43], v[140:143], v[200:203], v[40:43]
	v_mfma_f32_16x16x32_bf16 v[28:31], v[76:79], v[208:211], v[28:31]
	v_mfma_f32_16x16x32_bf16 v[24:27], v[140:143], v[208:211], v[24:27]
	v_mfma_f32_16x16x32_bf16 v[12:15], v[76:79], v[216:219], v[12:15]
	v_mfma_f32_16x16x32_bf16 v[8:11], v[140:143], v[216:219], v[8:11]
	s_setprio 0
	s_setprio 1
	v_mfma_f32_16x16x32_bf16 v[52:55], v[144:147], v[160:163], v[52:55]
	v_mfma_f32_16x16x32_bf16 v[48:51], v[152:155], v[160:163], v[48:51]
	v_mfma_f32_16x16x32_bf16 v[36:39], v[144:147], v[196:199], v[36:39]
	v_mfma_f32_16x16x32_bf16 v[32:35], v[152:155], v[196:199], v[32:35]
	v_mfma_f32_16x16x32_bf16 v[20:23], v[144:147], v[204:207], v[20:23]
	v_mfma_f32_16x16x32_bf16 v[16:19], v[152:155], v[204:207], v[16:19]
	v_mfma_f32_16x16x32_bf16 v[4:7], v[144:147], v[212:215], v[4:7]
	v_mfma_f32_16x16x32_bf16 v[0:3], v[152:155], v[212:215], v[0:3]
	v_mfma_f32_16x16x32_bf16 v[52:55], v[148:151], v[164:167], v[52:55]
	v_mfma_f32_16x16x32_bf16 v[48:51], v[156:159], v[164:167], v[48:51]
	v_mfma_f32_16x16x32_bf16 v[36:39], v[148:151], v[200:203], v[36:39]
	v_mfma_f32_16x16x32_bf16 v[32:35], v[156:159], v[200:203], v[32:35]
	v_mfma_f32_16x16x32_bf16 v[20:23], v[148:151], v[208:211], v[20:23]
	v_mfma_f32_16x16x32_bf16 v[16:19], v[156:159], v[208:211], v[16:19]
	v_mfma_f32_16x16x32_bf16 v[4:7], v[148:151], v[216:219], v[4:7]
	v_mfma_f32_16x16x32_bf16 v[0:3], v[156:159], v[216:219], v[0:3]
	s_setprio 0
	s_barrier
	s_add_u32 s38, s38, 0x100
	s_addc_u32 s39, s39, 0
	s_add_u32 s26, s26, 0x100
	s_addc_u32 s27, s27, 0
	s_cmp_ge_u32 s51, s44
	s_mov_b32 s14, s51
	s_cbranch_scc0 .LBB0_311
	s_and_b64 vcc, exec, s[6:7]
	s_cbranch_vccz .LBB0_314
	s_barrier
